# P0 conv-call rotation v3: workgroups 0-47 (three activation iterations) run only the one unavoidable conversion call
# speedup vs baseline: 1.0040x; 1.0040x over previous
.LBB0_123:
	s_or_b64 exec, exec, s[6:7]
	s_add_i32 s30, s97, 208
	s_and_b32 s30, s30, 0xff
	v_lshl_add_u32 v36, s30, 9, v202
	s_mov_b32 s0, 0x8000
	v_cmp_gt_i32_e64 s[6:7], s0, v36
	s_and_saveexec_b64 s[0:1], s[6:7]
	v_readlane_b32 s36, v246, 22
	v_readlane_b32 s46, v246, 32
	v_readlane_b32 s47, v246, 33
	v_readlane_b32 s37, v246, 23
	v_readlane_b32 s38, v246, 24
	v_readlane_b32 s39, v246, 25
	v_readlane_b32 s40, v246, 26
	v_readlane_b32 s41, v246, 27
	v_readlane_b32 s42, v246, 28
	v_readlane_b32 s43, v246, 29
	v_readlane_b32 s44, v246, 30
	v_readlane_b32 s45, v246, 31
	v_readlane_b32 s48, v246, 34
	v_readlane_b32 s49, v246, 35
	v_readlane_b32 s50, v246, 36
	v_readlane_b32 s51, v246, 37
	s_cbranch_execz .LBB0_126
	v_readlane_b32 s10, v246, 1
	s_add_u32 s8, s22, 0x580000
	v_lshlrev_b32_e32 v0, 3, v202
	v_readlane_b32 s11, v246, 2
	s_addc_u32 s9, s23, 0
	v_lshl_add_u32 v0, s30, 12, v0
	s_lshl_b32 s12, s10, 12
	s_mov_b64 s[10:11], 0
	s_movk_i32 s13, 0xffc0
	s_movk_i32 s14, 0x7fff
	v_mov_b32_e32 v1, v36

.LBB0_126:
	s_or_b64 exec, exec, s[0:1]
	s_add_i32 s30, s97, 208
	s_and_b32 s30, s30, 0xff
	v_lshl_add_u32 v36, s30, 9, v202
	s_movk_i32 s0, 0x4000
	v_cmp_gt_i32_e64 s[0:1], s0, v36
	s_and_saveexec_b64 s[10:11], s[0:1]
	s_cbranch_execz .LBB0_145
	s_add_u32 s12, s22, 0x780000
	v_readlane_b32 s36, v246, 22
	s_addc_u32 s13, s23, 0
	v_readlane_b32 s48, v246, 34
	v_readlane_b32 s49, v246, 35
	s_cmp_lg_u64 s[48:49], 0
	s_cselect_b64 s[8:9], -1, 0
	v_lshlrev_b32_e32 v0, 3, v202
	v_readlane_b32 s18, v246, 1
	v_lshl_add_u32 v37, s30, 12, v0
	v_readlane_b32 s19, v246, 2
	v_cndmask_b32_e64 v0, 0, 1, s[8:9]
	s_mov_b64 s[14:15], 0
	s_lshl_b32 s17, s18, 12
	s_movk_i32 s18, 0xffc0
	v_cmp_ne_u32_e64 s[8:9], 1, v0
	s_movk_i32 s19, 0x3fff
	v_mov_b32_e32 v38, v36
	v_readlane_b32 s37, v246, 23
	v_readlane_b32 s38, v246, 24
	v_readlane_b32 s39, v246, 25
	v_readlane_b32 s40, v246, 26
	v_readlane_b32 s41, v246, 27
	v_readlane_b32 s42, v246, 28
	v_readlane_b32 s43, v246, 29
	v_readlane_b32 s44, v246, 30
	v_readlane_b32 s45, v246, 31
	v_readlane_b32 s46, v246, 32
	v_readlane_b32 s47, v246, 33
	v_readlane_b32 s50, v246, 36
	v_readlane_b32 s51, v246, 37
	s_branch .LBB0_129

.LBB0_145:
	s_or_b64 exec, exec, s[10:11]
	s_add_i32 s30, s97, 144
	s_and_b32 s30, s30, 0xff
	v_lshl_add_u32 v36, s30, 9, v202
	s_mov_b32 s96, 0x8000
	v_cmp_gt_i32_e64 s[6:7], s96, v36
	s_and_saveexec_b64 s[8:9], s[6:7]
	s_cbranch_execz .LBB0_164
	s_add_u32 s10, s22, 0x880000
	v_readlane_b32 s36, v246, 22
	s_addc_u32 s11, s23, 0
	v_readlane_b32 s50, v246, 36
	v_readlane_b32 s51, v246, 37
	s_cmp_lg_u64 s[50:51], 0
	s_cselect_b64 s[6:7], -1, 0
	v_lshlrev_b32_e32 v0, 3, v202
	v_readlane_b32 s14, v246, 1
	v_lshl_add_u32 v37, s30, 12, v0
	v_readlane_b32 s15, v246, 2
	v_cndmask_b32_e64 v0, 0, 1, s[6:7]
	s_mov_b64 s[12:13], 0
	s_lshl_b32 s14, s14, 12
	s_movk_i32 s15, 0xffc0
	v_cmp_ne_u32_e64 s[6:7], 1, v0
	s_movk_i32 s17, 0x7fff
	v_mov_b32_e32 v38, v36
	v_readlane_b32 s37, v246, 23
	v_readlane_b32 s38, v246, 24
	v_readlane_b32 s39, v246, 25
	v_readlane_b32 s40, v246, 26
	v_readlane_b32 s41, v246, 27
	v_readlane_b32 s42, v246, 28
	v_readlane_b32 s43, v246, 29
	v_readlane_b32 s44, v246, 30
	v_readlane_b32 s45, v246, 31
	v_readlane_b32 s46, v246, 32
	v_readlane_b32 s47, v246, 33
	v_readlane_b32 s48, v246, 34
	v_readlane_b32 s49, v246, 35
	s_branch .LBB0_148

.LBB0_164:
	s_or_b64 exec, exec, s[8:9]
	s_add_i32 s30, s97, 32
	s_and_b32 s30, s30, 0xff
	v_lshl_add_u32 v36, s30, 9, v202
	s_movk_i32 s96, 0x4000
	v_cmp_gt_i32_e64 s[0:1], s96, v36
	s_and_saveexec_b64 s[6:7], s[0:1]
	v_readlane_b32 s36, v246, 38
	v_readlane_b32 s44, v246, 46
	v_readlane_b32 s45, v246, 47
	v_readlane_b32 s37, v246, 39
	v_readlane_b32 s38, v246, 40
	v_readlane_b32 s39, v246, 41
	v_readlane_b32 s40, v246, 42
	v_readlane_b32 s41, v246, 43
	v_readlane_b32 s42, v246, 44
	v_readlane_b32 s43, v246, 45
	v_readlane_b32 s46, v246, 48
	v_readlane_b32 s47, v246, 49
	v_readlane_b32 s48, v246, 50
	v_readlane_b32 s49, v246, 51
	v_readlane_b32 s50, v246, 52
	v_readlane_b32 s51, v246, 53
	s_cbranch_execz .LBB0_167
	v_readlane_b32 s8, v246, 1
	s_add_u32 s0, s22, 0xa80000
	v_lshlrev_b32_e32 v0, 3, v202
	v_readlane_b32 s9, v246, 2
	s_addc_u32 s1, s23, 0
	v_lshl_add_u32 v0, s30, 12, v0
	s_lshl_b32 s10, s8, 12
	s_mov_b64 s[8:9], 0
	s_movk_i32 s11, 0xffc0
	s_movk_i32 s12, 0x3fff
	v_mov_b32_e32 v1, v36
